# ssd inner loop with transposed xdt/a LDS layout (one b128 per 4 steps) inside the original chunk structure
# baseline (speedup 1.0000x reference)
; __device__ __forceinline__ void ssd_scan_unit(CP p, int l, int u, char* smem) {
;     ...
;     for (int s = 0; s < 16; ++s) {
;       const float* sb = cb + (s + 1) * SST;
;       const float4 B0n = *reinterpret_cast<const float4*>(sb + j * 4), B1n = *reinterpret_cast<const float4*>(sb + 64 + j * 4);
;       const float4 C0n = *reinterpret_cast<const float4*>(sb + 128 + j * 4), C1n = *reinterpret_cast<const float4*>(sb + 192 + j * 4);
;       const float xdtn = sb[256 + prow], xrn = sb[272 + prow], an = sb[288];
;       __builtin_amdgcn_sched_barrier(0);
;       hs[0] = fmaf(a, hs[0], xdt * B0.x); hs[1] = fmaf(a, hs[1], xdt * B0.y); hs[2] = fmaf(a, hs[2], xdt * B0.z); hs[3] = fmaf(a, hs[3], xdt * B0.w);
;       hs[4] = fmaf(a, hs[4], xdt * B1.x); hs[5] = fmaf(a, hs[5], xdt * B1.y); hs[6] = fmaf(a, hs[6], xdt * B1.z); hs[7] = fmaf(a, hs[7], xdt * B1.w);
;       float y = hs[0] * C0.x + hs[1] * C0.y + hs[2] * C0.z + hs[3] * C0.w + hs[4] * C1.x + hs[5] * C1.y + hs[6] * C1.z + hs[7] * C1.w;
;       y = allreduce16(y);
;       y = fmaf(Dh, xr, y);
;       if (j == s) ykeep = y;
;       B0 = B0n; B1 = B1n; C0 = C0n; C1 = C1n; xdt = xdtn; xr = xrn; a = an;
;     }
.LBB0_546:
	s_lshl_b32 s5, s4, 4
	v_mul_u32_u24_e32 v82, 0x4a0, v24
	v_lshl_add_u32 v81, v44, 2, v82
	s_bitcmp1_b32 s4, 0
	s_cselect_b32 s12, 0x4a00, 0
	s_cselect_b32 s13, 0x40, 0
	s_add_i32 s12, s63, s12
	s_add_i32 s13, s63, s13
	v_lshl_add_u32 v84, v56, 2, s12
	v_add_u32_e32 v85, s12, v82
	v_mov_b32_e32 v86, s13
	v_add_u32_e32 v87, s12, v81
	ds_read_b128 v[106:109], v85 offset:1024
	ds_read_b128 v[134:137], v86 offset:37888
	ds_read_b128 v[90:93], v84 offset:0
	ds_read_b128 v[94:97], v84 offset:256
	ds_read_b128 v[98:101], v84 offset:512
	ds_read_b128 v[102:105], v84 offset:768
	ds_read_b128 v[112:115], v84 offset:1184
	ds_read_b128 v[116:119], v84 offset:1440
	ds_read_b128 v[120:123], v84 offset:1696
	ds_read_b128 v[124:127], v84 offset:1952
	ds_read_b32 v186, v87 offset:1088
	s_waitcnt lgkmcnt(7)
	v_pk_mul_f32 v[176:177], v[90:91], v[106:107] op_sel_hi:[1,0]
	v_pk_mul_f32 v[178:179], v[92:93], v[106:107] op_sel_hi:[1,0]
	v_pk_mul_f32 v[180:181], v[94:95], v[106:107] op_sel_hi:[1,0]
	v_pk_mul_f32 v[182:183], v[96:97], v[106:107] op_sel_hi:[1,0]
	ds_read_b128 v[90:93], v84 offset:2368
	ds_read_b128 v[94:97], v84 offset:2624
	s_waitcnt lgkmcnt(5)
	v_pk_fma_f32 v[32:33], v[134:135], v[32:33], v[176:177] op_sel_hi:[0,1,1]
	v_pk_fma_f32 v[38:39], v[134:135], v[38:39], v[178:179] op_sel_hi:[0,1,1]
	v_pk_fma_f32 v[36:37], v[134:135], v[36:37], v[180:181] op_sel_hi:[0,1,1]
	v_pk_fma_f32 v[34:35], v[134:135], v[34:35], v[182:183] op_sel_hi:[0,1,1]
	v_pk_mul_f32 v[184:185], v[32:33], v[98:99]
	v_pk_mul_f32 v[176:177], v[112:113], v[106:107] op_sel:[0,1]
	v_pk_fma_f32 v[184:185], v[38:39], v[100:101], v[184:185]
	v_pk_mul_f32 v[178:179], v[114:115], v[106:107] op_sel:[0,1]
	v_pk_fma_f32 v[184:185], v[36:37], v[102:103], v[184:185]
	v_pk_mul_f32 v[180:181], v[116:117], v[106:107] op_sel:[0,1]
	v_pk_fma_f32 v[184:185], v[34:35], v[104:105], v[184:185]
	v_pk_mul_f32 v[182:183], v[118:119], v[106:107] op_sel:[0,1]
	v_add_f32_e32 v160, v184, v185
	ds_read_b128 v[112:115], v84 offset:3552
	ds_read_b128 v[116:119], v84 offset:3808
	ds_read_b128 v[98:101], v84 offset:2880
	ds_read_b128 v[102:105], v84 offset:3136
	ds_read_b128 v[128:131], v85 offset:1040
	ds_read_b128 v[138:141], v86 offset:37904
	s_waitcnt lgkmcnt(6)
	v_pk_fma_f32 v[32:33], v[134:135], v[32:33], v[176:177] op_sel:[1,0,0]
	v_pk_fma_f32 v[38:39], v[134:135], v[38:39], v[178:179] op_sel:[1,0,0]
	v_pk_fma_f32 v[36:37], v[134:135], v[36:37], v[180:181] op_sel:[1,0,0]
	v_pk_fma_f32 v[34:35], v[134:135], v[34:35], v[182:183] op_sel:[1,0,0]
	v_pk_mul_f32 v[184:185], v[32:33], v[120:121]
	v_pk_mul_f32 v[176:177], v[90:91], v[108:109] op_sel_hi:[1,0]
	v_pk_fma_f32 v[184:185], v[38:39], v[122:123], v[184:185]
	v_pk_mul_f32 v[178:179], v[92:93], v[108:109] op_sel_hi:[1,0]
	v_pk_fma_f32 v[184:185], v[36:37], v[124:125], v[184:185]
	v_pk_mul_f32 v[180:181], v[94:95], v[108:109] op_sel_hi:[1,0]
	v_pk_fma_f32 v[184:185], v[34:35], v[126:127], v[184:185]
	v_pk_mul_f32 v[182:183], v[96:97], v[108:109] op_sel_hi:[1,0]
	v_add_f32_e32 v161, v184, v185
	ds_read_b128 v[90:93], v84 offset:4736
	ds_read_b128 v[94:97], v84 offset:4992
	ds_read_b128 v[120:123], v84 offset:4064
	ds_read_b128 v[124:127], v84 offset:4320
	s_waitcnt lgkmcnt(6)
	v_pk_fma_f32 v[32:33], v[136:137], v[32:33], v[176:177] op_sel_hi:[0,1,1]
	v_pk_fma_f32 v[38:39], v[136:137], v[38:39], v[178:179] op_sel_hi:[0,1,1]
	v_pk_fma_f32 v[36:37], v[136:137], v[36:37], v[180:181] op_sel_hi:[0,1,1]
	v_pk_fma_f32 v[34:35], v[136:137], v[34:35], v[182:183] op_sel_hi:[0,1,1]
	v_pk_mul_f32 v[184:185], v[32:33], v[98:99]
	v_pk_mul_f32 v[176:177], v[112:113], v[108:109] op_sel:[0,1]
	v_pk_fma_f32 v[184:185], v[38:39], v[100:101], v[184:185]
	v_pk_mul_f32 v[178:179], v[114:115], v[108:109] op_sel:[0,1]
	v_pk_fma_f32 v[184:185], v[36:37], v[102:103], v[184:185]
	v_pk_mul_f32 v[180:181], v[116:117], v[108:109] op_sel:[0,1]
	v_pk_fma_f32 v[184:185], v[34:35], v[104:105], v[184:185]
	v_pk_mul_f32 v[182:183], v[118:119], v[108:109] op_sel:[0,1]
	v_add_f32_e32 v162, v184, v185
	ds_read_b128 v[112:115], v84 offset:5920
	ds_read_b128 v[116:119], v84 offset:6176
	ds_read_b128 v[98:101], v84 offset:5248
	ds_read_b128 v[102:105], v84 offset:5504
	s_waitcnt lgkmcnt(4)
	v_pk_fma_f32 v[32:33], v[136:137], v[32:33], v[176:177] op_sel:[1,0,0]
	v_pk_fma_f32 v[38:39], v[136:137], v[38:39], v[178:179] op_sel:[1,0,0]
	v_pk_fma_f32 v[36:37], v[136:137], v[36:37], v[180:181] op_sel:[1,0,0]
	v_pk_fma_f32 v[34:35], v[136:137], v[34:35], v[182:183] op_sel:[1,0,0]
	v_pk_mul_f32 v[184:185], v[32:33], v[120:121]
	v_pk_mul_f32 v[176:177], v[90:91], v[128:129] op_sel_hi:[1,0]
	v_pk_fma_f32 v[184:185], v[38:39], v[122:123], v[184:185]
	v_pk_mul_f32 v[178:179], v[92:93], v[128:129] op_sel_hi:[1,0]
	v_pk_fma_f32 v[184:185], v[36:37], v[124:125], v[184:185]
	v_pk_mul_f32 v[180:181], v[94:95], v[128:129] op_sel_hi:[1,0]
	v_pk_fma_f32 v[184:185], v[34:35], v[126:127], v[184:185]
	v_pk_mul_f32 v[182:183], v[96:97], v[128:129] op_sel_hi:[1,0]
	v_add_f32_e32 v163, v184, v185
	ds_read_b128 v[90:93], v84 offset:7104
	ds_read_b128 v[94:97], v84 offset:7360
	ds_read_b128 v[120:123], v84 offset:6432
	ds_read_b128 v[124:127], v84 offset:6688
	s_waitcnt lgkmcnt(4)
; __device__ __forceinline__ float bf2f(bf16_t v) { return __uint_as_float(((unsigned)v) << 16); }
; __device__ __forceinline__ float lo2f(unsigned w) { return __uint_as_float(w << 16); }
; __device__ __forceinline__ float hi2f(unsigned w) { return __uint_as_float(w & 0xffff0000u); }
; __device__ __forceinline__ void ssd_scan_unit(CP p, int l, int u, char* smem) {
;     ...
;   auto lwrite = [&](int bi) {
; #pragma unroll
;     for (int x = 0; x < 2; ++x) {
;       const int e = tid + x * 256, tok = e >> 5, rem = e & 31, which = rem >> 4, part = rem & 15;
;       float* d = buf + bi * 16 * SST + tok * SST + which * 128 + part * 8;
;       *reinterpret_cast<float4*>(d) = make_float4(lo2f(st[x].x), hi2f(st[x].x), lo2f(st[x].y), hi2f(st[x].y));
;       *reinterpret_cast<float4*>(d + 4) = make_float4(lo2f(st[x].z), hi2f(st[x].z), lo2f(st[x].w), hi2f(st[x].w));
;     }
;     {
;       const int tok = tid >> 4, pp = tid & 15;
;       float* d = buf + bi * 16 * SST + tok * SST;
;       const float stx = bf2f(stxr);
;       d[256 + pp] = stx * stdt;
;       d[272 + pp] = stx;
;       if (pp == 0) d[288] = __expf(stdt * Ah);
;     }
;   };
;     ...
;     for (int s = 0; s < 16; ++s) {
;       const float* sb = cb + (s + 1) * SST;
;       const float4 B0n = *reinterpret_cast<const float4*>(sb + j * 4), B1n = *reinterpret_cast<const float4*>(sb + 64 + j * 4);
;       const float4 C0n = *reinterpret_cast<const float4*>(sb + 128 + j * 4), C1n = *reinterpret_cast<const float4*>(sb + 192 + j * 4);
;       const float xdtn = sb[256 + prow], xrn = sb[272 + prow], an = sb[288];
;       __builtin_amdgcn_sched_barrier(0);
;       hs[0] = fmaf(a, hs[0], xdt * B0.x); hs[1] = fmaf(a, hs[1], xdt * B0.y); hs[2] = fmaf(a, hs[2], xdt * B0.z); hs[3] = fmaf(a, hs[3], xdt * B0.w);
;       hs[4] = fmaf(a, hs[4], xdt * B1.x); hs[5] = fmaf(a, hs[5], xdt * B1.y); hs[6] = fmaf(a, hs[6], xdt * B1.z); hs[7] = fmaf(a, hs[7], xdt * B1.w);
;       float y = hs[0] * C0.x + hs[1] * C0.y + hs[2] * C0.z + hs[3] * C0.w + hs[4] * C1.x + hs[5] * C1.y + hs[6] * C1.z + hs[7] * C1.w;
;       y = allreduce16(y);
;       y = fmaf(Dh, xr, y);
;       if (j == s) ykeep = y;
;       B0 = B0n; B1 = B1n; C0 = C0n; C1 = C1n; xdt = xdtn; xr = xrn; a = an;
;     }
	v_pk_fma_f32 v[32:33], v[138:139], v[32:33], v[176:177] op_sel_hi:[0,1,1]
	v_pk_fma_f32 v[38:39], v[138:139], v[38:39], v[178:179] op_sel_hi:[0,1,1]
	v_pk_fma_f32 v[36:37], v[138:139], v[36:37], v[180:181] op_sel_hi:[0,1,1]
	v_pk_fma_f32 v[34:35], v[138:139], v[34:35], v[182:183] op_sel_hi:[0,1,1]
	v_pk_mul_f32 v[184:185], v[32:33], v[98:99]
	v_pk_mul_f32 v[176:177], v[112:113], v[128:129] op_sel:[0,1]
	v_pk_fma_f32 v[184:185], v[38:39], v[100:101], v[184:185]
	v_pk_mul_f32 v[178:179], v[114:115], v[128:129] op_sel:[0,1]
	v_pk_fma_f32 v[184:185], v[36:37], v[102:103], v[184:185]
	v_pk_mul_f32 v[180:181], v[116:117], v[128:129] op_sel:[0,1]
	v_pk_fma_f32 v[184:185], v[34:35], v[104:105], v[184:185]
	v_pk_mul_f32 v[182:183], v[118:119], v[128:129] op_sel:[0,1]
	v_add_f32_e32 v164, v184, v185
	ds_read_b128 v[112:115], v84 offset:8288
	ds_read_b128 v[116:119], v84 offset:8544
	ds_read_b128 v[98:101], v84 offset:7616
	ds_read_b128 v[102:105], v84 offset:7872
	ds_read_b128 v[106:109], v85 offset:1056
	ds_read_b128 v[134:137], v86 offset:37920
	s_waitcnt lgkmcnt(6)
	v_pk_fma_f32 v[32:33], v[138:139], v[32:33], v[176:177] op_sel:[1,0,0]
	v_pk_fma_f32 v[38:39], v[138:139], v[38:39], v[178:179] op_sel:[1,0,0]
	v_pk_fma_f32 v[36:37], v[138:139], v[36:37], v[180:181] op_sel:[1,0,0]
	v_pk_fma_f32 v[34:35], v[138:139], v[34:35], v[182:183] op_sel:[1,0,0]
	v_pk_mul_f32 v[184:185], v[32:33], v[120:121]
	v_pk_mul_f32 v[176:177], v[90:91], v[130:131] op_sel_hi:[1,0]
	v_pk_fma_f32 v[184:185], v[38:39], v[122:123], v[184:185]
	v_pk_mul_f32 v[178:179], v[92:93], v[130:131] op_sel_hi:[1,0]
	v_pk_fma_f32 v[184:185], v[36:37], v[124:125], v[184:185]
	v_pk_mul_f32 v[180:181], v[94:95], v[130:131] op_sel_hi:[1,0]
	v_pk_fma_f32 v[184:185], v[34:35], v[126:127], v[184:185]
	v_pk_mul_f32 v[182:183], v[96:97], v[130:131] op_sel_hi:[1,0]
	v_add_f32_e32 v165, v184, v185
	ds_read_b128 v[90:93], v84 offset:9472
	ds_read_b128 v[94:97], v84 offset:9728
	ds_read_b128 v[120:123], v84 offset:8800
	ds_read_b128 v[124:127], v84 offset:9056
	s_waitcnt lgkmcnt(6)
	v_pk_fma_f32 v[32:33], v[140:141], v[32:33], v[176:177] op_sel_hi:[0,1,1]
	v_pk_fma_f32 v[38:39], v[140:141], v[38:39], v[178:179] op_sel_hi:[0,1,1]
	v_pk_fma_f32 v[36:37], v[140:141], v[36:37], v[180:181] op_sel_hi:[0,1,1]
	v_pk_fma_f32 v[34:35], v[140:141], v[34:35], v[182:183] op_sel_hi:[0,1,1]
	v_pk_mul_f32 v[184:185], v[32:33], v[98:99]
	v_pk_mul_f32 v[176:177], v[112:113], v[130:131] op_sel:[0,1]
	v_pk_fma_f32 v[184:185], v[38:39], v[100:101], v[184:185]
	v_pk_mul_f32 v[178:179], v[114:115], v[130:131] op_sel:[0,1]
	v_pk_fma_f32 v[184:185], v[36:37], v[102:103], v[184:185]
	v_pk_mul_f32 v[180:181], v[116:117], v[130:131] op_sel:[0,1]
	v_pk_fma_f32 v[184:185], v[34:35], v[104:105], v[184:185]
	v_pk_mul_f32 v[182:183], v[118:119], v[130:131] op_sel:[0,1]
	v_add_f32_e32 v166, v184, v185
	ds_read_b128 v[112:115], v84 offset:10656
	ds_read_b128 v[116:119], v84 offset:10912
	ds_read_b128 v[98:101], v84 offset:9984
	ds_read_b128 v[102:105], v84 offset:10240
	s_waitcnt lgkmcnt(4)
	v_pk_fma_f32 v[32:33], v[140:141], v[32:33], v[176:177] op_sel:[1,0,0]
	v_pk_fma_f32 v[38:39], v[140:141], v[38:39], v[178:179] op_sel:[1,0,0]
	v_pk_fma_f32 v[36:37], v[140:141], v[36:37], v[180:181] op_sel:[1,0,0]
	v_pk_fma_f32 v[34:35], v[140:141], v[34:35], v[182:183] op_sel:[1,0,0]
	v_pk_mul_f32 v[184:185], v[32:33], v[120:121]
	v_pk_mul_f32 v[176:177], v[90:91], v[106:107] op_sel_hi:[1,0]
	v_pk_fma_f32 v[184:185], v[38:39], v[122:123], v[184:185]
	v_pk_mul_f32 v[178:179], v[92:93], v[106:107] op_sel_hi:[1,0]
	v_pk_fma_f32 v[184:185], v[36:37], v[124:125], v[184:185]
	v_pk_mul_f32 v[180:181], v[94:95], v[106:107] op_sel_hi:[1,0]
	v_pk_fma_f32 v[184:185], v[34:35], v[126:127], v[184:185]
	v_pk_mul_f32 v[182:183], v[96:97], v[106:107] op_sel_hi:[1,0]
	v_add_f32_e32 v167, v184, v185
	ds_read_b128 v[90:93], v84 offset:11840
	ds_read_b128 v[94:97], v84 offset:12096
	ds_read_b128 v[120:123], v84 offset:11168
	ds_read_b128 v[124:127], v84 offset:11424
	s_waitcnt lgkmcnt(4)
	v_pk_fma_f32 v[32:33], v[134:135], v[32:33], v[176:177] op_sel_hi:[0,1,1]
	v_pk_fma_f32 v[38:39], v[134:135], v[38:39], v[178:179] op_sel_hi:[0,1,1]
	v_pk_fma_f32 v[36:37], v[134:135], v[36:37], v[180:181] op_sel_hi:[0,1,1]
	v_pk_fma_f32 v[34:35], v[134:135], v[34:35], v[182:183] op_sel_hi:[0,1,1]
	v_pk_mul_f32 v[184:185], v[32:33], v[98:99]
	v_pk_mul_f32 v[176:177], v[112:113], v[106:107] op_sel:[0,1]
	v_pk_fma_f32 v[184:185], v[38:39], v[100:101], v[184:185]
	v_pk_mul_f32 v[178:179], v[114:115], v[106:107] op_sel:[0,1]
	v_pk_fma_f32 v[184:185], v[36:37], v[102:103], v[184:185]
	v_pk_mul_f32 v[180:181], v[116:117], v[106:107] op_sel:[0,1]
	v_pk_fma_f32 v[184:185], v[34:35], v[104:105], v[184:185]
	v_pk_mul_f32 v[182:183], v[118:119], v[106:107] op_sel:[0,1]
	v_add_f32_e32 v168, v184, v185
	ds_read_b128 v[112:115], v84 offset:13024
	ds_read_b128 v[116:119], v84 offset:13280
	ds_read_b128 v[98:101], v84 offset:12352
	ds_read_b128 v[102:105], v84 offset:12608
	ds_read_b128 v[128:131], v85 offset:1072
	ds_read_b128 v[138:141], v86 offset:37936
	s_waitcnt lgkmcnt(6)
	v_pk_fma_f32 v[32:33], v[134:135], v[32:33], v[176:177] op_sel:[1,0,0]
	v_pk_fma_f32 v[38:39], v[134:135], v[38:39], v[178:179] op_sel:[1,0,0]
	v_pk_fma_f32 v[36:37], v[134:135], v[36:37], v[180:181] op_sel:[1,0,0]
	v_pk_fma_f32 v[34:35], v[134:135], v[34:35], v[182:183] op_sel:[1,0,0]
	v_pk_mul_f32 v[184:185], v[32:33], v[120:121]
	v_pk_mul_f32 v[176:177], v[90:91], v[108:109] op_sel_hi:[1,0]
	v_pk_fma_f32 v[184:185], v[38:39], v[122:123], v[184:185]
	v_pk_mul_f32 v[178:179], v[92:93], v[108:109] op_sel_hi:[1,0]
	v_pk_fma_f32 v[184:185], v[36:37], v[124:125], v[184:185]
	v_pk_mul_f32 v[180:181], v[94:95], v[108:109] op_sel_hi:[1,0]
	v_pk_fma_f32 v[184:185], v[34:35], v[126:127], v[184:185]
	v_pk_mul_f32 v[182:183], v[96:97], v[108:109] op_sel_hi:[1,0]
	v_add_f32_e32 v169, v184, v185
	ds_read_b128 v[90:93], v84 offset:14208
	ds_read_b128 v[94:97], v84 offset:14464
	ds_read_b128 v[120:123], v84 offset:13536
	ds_read_b128 v[124:127], v84 offset:13792
	s_waitcnt lgkmcnt(6)
; __device__ __forceinline__ void ssd_scan_unit(CP p, int l, int u, char* smem) {
;     ...
;     for (int s = 0; s < 16; ++s) {
;       const float* sb = cb + (s + 1) * SST;
;       const float4 B0n = *reinterpret_cast<const float4*>(sb + j * 4), B1n = *reinterpret_cast<const float4*>(sb + 64 + j * 4);
;       const float4 C0n = *reinterpret_cast<const float4*>(sb + 128 + j * 4), C1n = *reinterpret_cast<const float4*>(sb + 192 + j * 4);
;       const float xdtn = sb[256 + prow], xrn = sb[272 + prow], an = sb[288];
;       __builtin_amdgcn_sched_barrier(0);
;       hs[0] = fmaf(a, hs[0], xdt * B0.x); hs[1] = fmaf(a, hs[1], xdt * B0.y); hs[2] = fmaf(a, hs[2], xdt * B0.z); hs[3] = fmaf(a, hs[3], xdt * B0.w);
;       hs[4] = fmaf(a, hs[4], xdt * B1.x); hs[5] = fmaf(a, hs[5], xdt * B1.y); hs[6] = fmaf(a, hs[6], xdt * B1.z); hs[7] = fmaf(a, hs[7], xdt * B1.w);
;       float y = hs[0] * C0.x + hs[1] * C0.y + hs[2] * C0.z + hs[3] * C0.w + hs[4] * C1.x + hs[5] * C1.y + hs[6] * C1.z + hs[7] * C1.w;
;       y = allreduce16(y);
;       y = fmaf(Dh, xr, y);
;       if (j == s) ykeep = y;
;       B0 = B0n; B1 = B1n; C0 = C0n; C1 = C1n; xdt = xdtn; xr = xrn; a = an;
;     }
	v_pk_fma_f32 v[32:33], v[136:137], v[32:33], v[176:177] op_sel_hi:[0,1,1]
	v_pk_fma_f32 v[38:39], v[136:137], v[38:39], v[178:179] op_sel_hi:[0,1,1]
	v_pk_fma_f32 v[36:37], v[136:137], v[36:37], v[180:181] op_sel_hi:[0,1,1]
	v_pk_fma_f32 v[34:35], v[136:137], v[34:35], v[182:183] op_sel_hi:[0,1,1]
	v_pk_mul_f32 v[184:185], v[32:33], v[98:99]
	v_pk_mul_f32 v[176:177], v[112:113], v[108:109] op_sel:[0,1]
	v_pk_fma_f32 v[184:185], v[38:39], v[100:101], v[184:185]
	v_pk_mul_f32 v[178:179], v[114:115], v[108:109] op_sel:[0,1]
	v_pk_fma_f32 v[184:185], v[36:37], v[102:103], v[184:185]
	v_pk_mul_f32 v[180:181], v[116:117], v[108:109] op_sel:[0,1]
	v_pk_fma_f32 v[184:185], v[34:35], v[104:105], v[184:185]
	v_pk_mul_f32 v[182:183], v[118:119], v[108:109] op_sel:[0,1]
	v_add_f32_e32 v170, v184, v185
	ds_read_b128 v[112:115], v84 offset:15392
	ds_read_b128 v[116:119], v84 offset:15648
	ds_read_b128 v[98:101], v84 offset:14720
	ds_read_b128 v[102:105], v84 offset:14976
	s_waitcnt lgkmcnt(4)
	v_pk_fma_f32 v[32:33], v[136:137], v[32:33], v[176:177] op_sel:[1,0,0]
	v_pk_fma_f32 v[38:39], v[136:137], v[38:39], v[178:179] op_sel:[1,0,0]
	v_pk_fma_f32 v[36:37], v[136:137], v[36:37], v[180:181] op_sel:[1,0,0]
	v_pk_fma_f32 v[34:35], v[136:137], v[34:35], v[182:183] op_sel:[1,0,0]
	v_pk_mul_f32 v[184:185], v[32:33], v[120:121]
	v_pk_mul_f32 v[176:177], v[90:91], v[128:129] op_sel_hi:[1,0]
	v_pk_fma_f32 v[184:185], v[38:39], v[122:123], v[184:185]
	v_pk_mul_f32 v[178:179], v[92:93], v[128:129] op_sel_hi:[1,0]
	v_pk_fma_f32 v[184:185], v[36:37], v[124:125], v[184:185]
	v_pk_mul_f32 v[180:181], v[94:95], v[128:129] op_sel_hi:[1,0]
	v_pk_fma_f32 v[184:185], v[34:35], v[126:127], v[184:185]
	v_pk_mul_f32 v[182:183], v[96:97], v[128:129] op_sel_hi:[1,0]
	v_add_f32_e32 v171, v184, v185
	ds_read_b128 v[90:93], v84 offset:16576
	ds_read_b128 v[94:97], v84 offset:16832
	ds_read_b128 v[120:123], v84 offset:15904
	ds_read_b128 v[124:127], v84 offset:16160
	s_waitcnt lgkmcnt(4)
	v_pk_fma_f32 v[32:33], v[138:139], v[32:33], v[176:177] op_sel_hi:[0,1,1]
	v_pk_fma_f32 v[38:39], v[138:139], v[38:39], v[178:179] op_sel_hi:[0,1,1]
	v_pk_fma_f32 v[36:37], v[138:139], v[36:37], v[180:181] op_sel_hi:[0,1,1]
	v_pk_fma_f32 v[34:35], v[138:139], v[34:35], v[182:183] op_sel_hi:[0,1,1]
	v_pk_mul_f32 v[184:185], v[32:33], v[98:99]
	v_pk_mul_f32 v[176:177], v[112:113], v[128:129] op_sel:[0,1]
	v_pk_fma_f32 v[184:185], v[38:39], v[100:101], v[184:185]
	v_pk_mul_f32 v[178:179], v[114:115], v[128:129] op_sel:[0,1]
	v_pk_fma_f32 v[184:185], v[36:37], v[102:103], v[184:185]
	v_pk_mul_f32 v[180:181], v[116:117], v[128:129] op_sel:[0,1]
	v_pk_fma_f32 v[184:185], v[34:35], v[104:105], v[184:185]
	v_pk_mul_f32 v[182:183], v[118:119], v[128:129] op_sel:[0,1]
	v_add_f32_e32 v172, v184, v185
	ds_read_b128 v[112:115], v84 offset:17760
	ds_read_b128 v[116:119], v84 offset:18016
	ds_read_b128 v[98:101], v84 offset:17088
	ds_read_b128 v[102:105], v84 offset:17344
	s_waitcnt lgkmcnt(4)
	v_pk_fma_f32 v[32:33], v[138:139], v[32:33], v[176:177] op_sel:[1,0,0]
	v_pk_fma_f32 v[38:39], v[138:139], v[38:39], v[178:179] op_sel:[1,0,0]
	v_pk_fma_f32 v[36:37], v[138:139], v[36:37], v[180:181] op_sel:[1,0,0]
	v_pk_fma_f32 v[34:35], v[138:139], v[34:35], v[182:183] op_sel:[1,0,0]
	v_pk_mul_f32 v[184:185], v[32:33], v[120:121]
	v_pk_mul_f32 v[176:177], v[90:91], v[130:131] op_sel_hi:[1,0]
	v_pk_fma_f32 v[184:185], v[38:39], v[122:123], v[184:185]
	v_pk_mul_f32 v[178:179], v[92:93], v[130:131] op_sel_hi:[1,0]
	v_pk_fma_f32 v[184:185], v[36:37], v[124:125], v[184:185]
	v_pk_mul_f32 v[180:181], v[94:95], v[130:131] op_sel_hi:[1,0]
	v_pk_fma_f32 v[184:185], v[34:35], v[126:127], v[184:185]
	v_pk_mul_f32 v[182:183], v[96:97], v[130:131] op_sel_hi:[1,0]
	v_add_f32_e32 v173, v184, v185
	ds_read_b128 v[120:123], v84 offset:18272
	ds_read_b128 v[124:127], v84 offset:18528
	s_waitcnt lgkmcnt(2)
	v_pk_fma_f32 v[32:33], v[140:141], v[32:33], v[176:177] op_sel_hi:[0,1,1]
	v_pk_fma_f32 v[38:39], v[140:141], v[38:39], v[178:179] op_sel_hi:[0,1,1]
	v_pk_fma_f32 v[36:37], v[140:141], v[36:37], v[180:181] op_sel_hi:[0,1,1]
	v_pk_fma_f32 v[34:35], v[140:141], v[34:35], v[182:183] op_sel_hi:[0,1,1]
	v_pk_mul_f32 v[184:185], v[32:33], v[98:99]
	v_pk_mul_f32 v[176:177], v[112:113], v[130:131] op_sel:[0,1]
	v_pk_fma_f32 v[184:185], v[38:39], v[100:101], v[184:185]
	v_pk_mul_f32 v[178:179], v[114:115], v[130:131] op_sel:[0,1]
	v_pk_fma_f32 v[184:185], v[36:37], v[102:103], v[184:185]
	v_pk_mul_f32 v[180:181], v[116:117], v[130:131] op_sel:[0,1]
	v_pk_fma_f32 v[184:185], v[34:35], v[104:105], v[184:185]
	v_pk_mul_f32 v[182:183], v[118:119], v[130:131] op_sel:[0,1]
	v_add_f32_e32 v174, v184, v185
	s_waitcnt lgkmcnt(0)
; __device__ __forceinline__ float bf2f(bf16_t v) { return __uint_as_float(((unsigned)v) << 16); }
; __device__ __forceinline__ bf16_t f2bf(float f) { return (bf16_t)(pack2(f, 0.f) & 0xffffu); }
; __device__ __forceinline__ float lo2f(unsigned w) { return __uint_as_float(w << 16); }
; __device__ __forceinline__ float hi2f(unsigned w) { return __uint_as_float(w & 0xffff0000u); }
; __device__ __forceinline__ void ssd_scan_unit(CP p, int l, int u, char* smem) {
;     ...
;   auto lwrite = [&](int bi) {
; #pragma unroll
;     for (int x = 0; x < 2; ++x) {
;       const int e = tid + x * 256, tok = e >> 5, rem = e & 31, which = rem >> 4, part = rem & 15;
;       float* d = buf + bi * 16 * SST + tok * SST + which * 128 + part * 8;
;       *reinterpret_cast<float4*>(d) = make_float4(lo2f(st[x].x), hi2f(st[x].x), lo2f(st[x].y), hi2f(st[x].y));
;       *reinterpret_cast<float4*>(d + 4) = make_float4(lo2f(st[x].z), hi2f(st[x].z), lo2f(st[x].w), hi2f(st[x].w));
;     }
;     {
;       const int tok = tid >> 4, pp = tid & 15;
;       float* d = buf + bi * 16 * SST + tok * SST;
;       const float stx = bf2f(stxr);
;       d[256 + pp] = stx * stdt;
;       d[272 + pp] = stx;
;       if (pp == 0) d[288] = __expf(stdt * Ah);
;     }
;   };
;     ...
;       if (j == s) ykeep = y;
;       B0 = B0n; B1 = B1n; C0 = C0n; C1 = C1n; xdt = xdtn; xr = xrn; a = an;
;     }
;     Y[(size_t)(rowof(b, c * 16) + j) * 1024 + h * 64 + q * 16 + prow] = f2bf(ykeep);
;     if (c + 1 < NCH) lwrite((c + 1) & 1);
	v_pk_fma_f32 v[32:33], v[140:141], v[32:33], v[176:177] op_sel:[1,0,0]
	v_pk_fma_f32 v[38:39], v[140:141], v[38:39], v[178:179] op_sel:[1,0,0]
	v_pk_fma_f32 v[36:37], v[140:141], v[36:37], v[180:181] op_sel:[1,0,0]
	v_pk_fma_f32 v[34:35], v[140:141], v[34:35], v[182:183] op_sel:[1,0,0]
	v_pk_mul_f32 v[184:185], v[32:33], v[120:121]
	v_pk_fma_f32 v[184:185], v[38:39], v[122:123], v[184:185]
	v_pk_fma_f32 v[184:185], v[36:37], v[124:125], v[184:185]
	v_pk_fma_f32 v[184:185], v[34:35], v[126:127], v[184:185]
	v_add_f32_e32 v175, v184, v185
	v_add_f32_dpp v160, v160, v160 row_ror:8 row_mask:0xf bank_mask:0x3 bound_ctrl:1
	v_add_f32_dpp v161, v161, v161 row_ror:8 row_mask:0xf bank_mask:0x3 bound_ctrl:1
	v_add_f32_dpp v162, v162, v162 row_ror:8 row_mask:0xf bank_mask:0x3 bound_ctrl:1
	v_add_f32_dpp v163, v163, v163 row_ror:8 row_mask:0xf bank_mask:0x3 bound_ctrl:1
	v_add_f32_dpp v164, v164, v164 row_ror:8 row_mask:0xf bank_mask:0x3 bound_ctrl:1
	v_add_f32_dpp v165, v165, v165 row_ror:8 row_mask:0xf bank_mask:0x3 bound_ctrl:1
	v_add_f32_dpp v166, v166, v166 row_ror:8 row_mask:0xf bank_mask:0x3 bound_ctrl:1
	v_add_f32_dpp v167, v167, v167 row_ror:8 row_mask:0xf bank_mask:0x3 bound_ctrl:1
	v_add_f32_dpp v160, v168, v168 row_ror:8 row_mask:0xf bank_mask:0xc bound_ctrl:1
	v_add_f32_dpp v161, v169, v169 row_ror:8 row_mask:0xf bank_mask:0xc bound_ctrl:1
	v_add_f32_dpp v162, v170, v170 row_ror:8 row_mask:0xf bank_mask:0xc bound_ctrl:1
	v_add_f32_dpp v163, v171, v171 row_ror:8 row_mask:0xf bank_mask:0xc bound_ctrl:1
	v_add_f32_dpp v164, v172, v172 row_ror:8 row_mask:0xf bank_mask:0xc bound_ctrl:1
	v_add_f32_dpp v165, v173, v173 row_ror:8 row_mask:0xf bank_mask:0xc bound_ctrl:1
	v_add_f32_dpp v166, v174, v174 row_ror:8 row_mask:0xf bank_mask:0xc bound_ctrl:1
	v_add_f32_dpp v167, v175, v175 row_ror:8 row_mask:0xf bank_mask:0xc bound_ctrl:1
	v_add_f32_dpp v160, v160, v160 row_half_mirror row_mask:0xf bank_mask:0x5 bound_ctrl:1
	v_add_f32_dpp v161, v161, v161 row_half_mirror row_mask:0xf bank_mask:0x5 bound_ctrl:1
	v_add_f32_dpp v162, v162, v162 row_half_mirror row_mask:0xf bank_mask:0x5 bound_ctrl:1
	v_add_f32_dpp v163, v163, v163 row_half_mirror row_mask:0xf bank_mask:0x5 bound_ctrl:1
	v_add_f32_dpp v160, v164, v164 row_half_mirror row_mask:0xf bank_mask:0xa bound_ctrl:1
	v_add_f32_dpp v161, v165, v165 row_half_mirror row_mask:0xf bank_mask:0xa bound_ctrl:1
	v_add_f32_dpp v162, v166, v166 row_half_mirror row_mask:0xf bank_mask:0xa bound_ctrl:1
	v_add_f32_dpp v163, v167, v167 row_half_mirror row_mask:0xf bank_mask:0xa bound_ctrl:1
	v_and_b32_e32 v188, 2, v44
	v_cmp_ne_u32_e32 vcc, 0, v188
	v_and_b32_e32 v188, 1, v44
	s_nop 0
	v_cndmask_b32_e32 v189, v160, v162, vcc
	v_cndmask_b32_e32 v190, v162, v160, vcc
	v_cndmask_b32_e32 v191, v161, v163, vcc
	v_cndmask_b32_e32 v192, v163, v161, vcc
	v_cmp_ne_u32_e32 vcc, 0, v188
	v_add_f32_dpp v160, v190, v189 quad_perm:[2,3,0,1] row_mask:0xf bank_mask:0xf bound_ctrl:1
	v_add_f32_dpp v161, v192, v191 quad_perm:[2,3,0,1] row_mask:0xf bank_mask:0xf bound_ctrl:1
	v_cndmask_b32_e32 v189, v160, v161, vcc
	v_cndmask_b32_e32 v190, v161, v160, vcc
	s_nop 1
	v_add_f32_dpp v187, v190, v189 quad_perm:[1,0,3,2] row_mask:0xf bank_mask:0xf bound_ctrl:1
	v_fma_f32 v60, v43, v186, v187
	s_add_i32 s5, s5, s11
	s_cmp_eq_u32 s4, 0
	s_cselect_b32 s4, s10, s5
	s_waitcnt lgkmcnt(2)
	v_or_b32_e32 v8, s4, v44
	v_ashrrev_i32_e32 v9, 31, v8
	v_lshlrev_b64 v[8:9], 11, v[8:9]
	v_cvt_pk_bf16_f32 v10, v60, s0
	v_lshl_add_u64 v[8:9], v[28:29], 0, v[8:9]
	s_and_b64 vcc, exec, s[2:3]
	global_store_short v[8:9], v10, off
	s_cbranch_vccz .LBB0_552
	s_bitcmp1_b32 s28, 0
	s_cselect_b32 s2, 0x4a00, 0
	s_cselect_b32 s5, 0x40, 0
	s_add_i32 s2, s63, s2
	v_lshl_add_u32 v8, v50, 2, s2
	v_add3_u32 v12, v8, v51, v52
	s_waitcnt vmcnt(4)
	v_lshlrev_b32_e32 v8, 16, v0
	v_and_b32_e32 v9, 0xffff0000, v0
	v_lshlrev_b32_e32 v10, 16, v1
	v_and_b32_e32 v11, 0xffff0000, v1
	ds_write_b128 v12, v[8:11]
	v_lshlrev_b32_e32 v8, 16, v2
	v_and_b32_e32 v9, 0xffff0000, v2
	v_lshlrev_b32_e32 v10, 16, v3
	v_and_b32_e32 v11, 0xffff0000, v3
	ds_write_b128 v12, v[8:11] offset:16
	v_lshl_add_u32 v8, v53, 2, s2
	v_add3_u32 v12, v8, v51, v52
	s_waitcnt vmcnt(3)
	v_lshlrev_b32_e32 v8, 16, v4
	v_and_b32_e32 v9, 0xffff0000, v4
	v_lshlrev_b32_e32 v10, 16, v5
	v_and_b32_e32 v11, 0xffff0000, v5
	ds_write_b128 v12, v[8:11]
	v_lshlrev_b32_e32 v8, 16, v6
	v_and_b32_e32 v9, 0xffff0000, v6
	v_lshlrev_b32_e32 v10, 16, v7
	v_and_b32_e32 v11, 0xffff0000, v7
	ds_write_b128 v12, v[8:11] offset:16
	v_lshl_add_u32 v8, v55, 2, s2
	s_waitcnt vmcnt(2)
	v_lshlrev_b32_e32 v9, 16, v49
	v_add_u32_e32 v11, s2, v83
	s_waitcnt vmcnt(1)
	v_mul_f32_e32 v10, v54, v9
	ds_write2_b32 v11, v10, v9 offset1:16
	s_and_saveexec_b64 s[2:3], s[38:39]
	s_cbranch_execz .LBB0_551
	v_mul_f32_e32 v9, v54, v46
	v_mul_f32_e32 v9, 0xbfb8aa3b, v9
	v_exp_f32_e32 v9, v9
	v_lshl_add_u32 v8, v45, 2, s63
	v_add_u32_e32 v8, s5, v8
	ds_write_b32 v8, v9 offset:37888
